# lat scan step: packed fp32 ops between MFMAs split into two single ops (37 sites, bit-identical)
# baseline (speedup 1.0000x reference)
.LBB0_320:
	v_add_u32_e32 v234, v206, v209
	v_add_u32_e32 v242, 0x5000, v234
	v_add_u32_e32 v234, 0x4800, v234
	ds_read2_b64 v[238:241], v234 offset0:8 offset1:12
	ds_read2_b64 v[234:237], v234 offset1:4
	ds_read2_b64 v[246:249], v242 offset0:40 offset1:44
	ds_read2_b64 v[242:245], v242 offset0:32 offset1:36
	v_add_u32_e32 v3, 0xb000, v205
	ds_read_b128 v[56:59], v204 offset:45056
	ds_read2_b32 v[166:167], v3 offset1:16
	ds_read_b128 v[52:55], v204 offset:45120
	ds_read_b128 v[48:51], v204 offset:45184
	ds_read2_b32 v[160:161], v3 offset0:32 offset1:48
	ds_read_b128 v[44:47], v204 offset:45248
	ds_read_b32 v220, v2 offset:45308
	ds_read_b128 v[74:77], v208 offset:27648
	ds_read_b128 v[78:81], v208 offset:28672
	v_cvt_pk_bf16_f32 v64, v24, v25
	v_cvt_pk_bf16_f32 v65, v26, v27
	v_cvt_pk_bf16_f32 v66, v4, v5
	v_cvt_pk_bf16_f32 v67, v6, v7
	v_cvt_pk_bf16_f32 v60, v8, v9
	v_cvt_pk_bf16_f32 v61, v10, v11
	s_waitcnt lgkmcnt(1)
	v_mfma_f32_16x16x32_bf16 v[74:77], v[74:77], v[64:67], 0
	v_cvt_pk_bf16_f32 v62, v12, v13
	v_cvt_pk_bf16_f32 v63, v14, v15
	s_mov_b32 s0, 0x5040100
	v_readlane_b32 s84, v254, 26
	s_waitcnt lgkmcnt(0)
	v_mfma_f32_16x16x32_bf16 v[74:77], v[78:81], v[60:63], v[74:77]
	s_waitcnt vmcnt(13)
	v_lshlrev_b32_e32 v78, 16, v72
	v_and_b32_e32 v79, 0xffff0000, v72
	v_lshlrev_b32_e32 v72, 16, v73
	v_and_b32_e32 v73, 0xffff0000, v73
	v_readlane_b32 s86, v254, 28
	s_nop 1
	v_sub_f32_e32 v158, v78, v74
	v_sub_f32_e32 v159, v79, v75
	v_sub_f32_e32 v156, v72, v76
	v_sub_f32_e32 v157, v73, v77
	ds_read_b128 v[72:75], v208 offset:29696
	ds_read_b128 v[76:79], v208 offset:30720
	s_waitcnt lgkmcnt(1)
	v_mfma_f32_16x16x32_bf16 v[72:75], v[72:75], v[64:67], 0
	v_readlane_b32 s87, v254, 29
	v_readlane_b32 s85, v254, 27
	v_add_u32_e32 v191, v213, v211
	s_waitcnt lgkmcnt(0)
	v_mfma_f32_16x16x32_bf16 v[72:75], v[76:79], v[60:63], v[72:75]
	s_waitcnt vmcnt(12)
	v_lshlrev_b32_e32 v76, 16, v70
	v_and_b32_e32 v77, 0xffff0000, v70
	v_lshlrev_b32_e32 v70, 16, v71
	v_and_b32_e32 v71, 0xffff0000, v71
	v_mov_b64_e32 v[110:111], s[86:87]
	s_nop 1
	v_sub_f32_e32 v154, v76, v72
	v_sub_f32_e32 v155, v77, v73
	v_sub_f32_e32 v150, v70, v74
	v_sub_f32_e32 v151, v71, v75
	ds_read_b128 v[70:73], v208 offset:31744
	ds_read_b128 v[74:77], v208 offset:32768
	s_waitcnt lgkmcnt(1)
	v_mfma_f32_16x16x32_bf16 v[70:73], v[70:73], v[64:67], 0
	v_mov_b64_e32 v[108:109], s[84:85]
	s_add_i32 s67, s67, -1
	s_mov_b64 s[80:81], 0
	s_waitcnt lgkmcnt(0)
	v_mfma_f32_16x16x32_bf16 v[70:73], v[74:77], v[60:63], v[70:73]
	s_waitcnt vmcnt(11)
	v_lshlrev_b32_e32 v74, 16, v68
	v_and_b32_e32 v75, 0xffff0000, v68
	v_lshlrev_b32_e32 v68, 16, v69
	v_and_b32_e32 v69, 0xffff0000, v69
	s_nop 2
	v_sub_f32_e32 v152, v74, v70
	v_sub_f32_e32 v153, v75, v71
	v_sub_f32_e32 v148, v68, v72
	v_sub_f32_e32 v149, v69, v73
	ds_read_b128 v[68:71], v208 offset:33792
	ds_read_b128 v[72:75], v208 offset:34816
	s_waitcnt lgkmcnt(1)
	v_mfma_f32_16x16x32_bf16 v[68:71], v[68:71], v[64:67], 0
	s_waitcnt lgkmcnt(0)
	v_mfma_f32_16x16x32_bf16 v[68:71], v[72:75], v[60:63], v[68:71]
	s_waitcnt vmcnt(10)
	v_lshlrev_b32_e32 v72, 16, v0
	v_and_b32_e32 v73, 0xffff0000, v0
	v_lshlrev_b32_e32 v0, 16, v1
	v_and_b32_e32 v1, 0xffff0000, v1
	v_cvt_pk_bf16_f32 v74, v154, v155
	s_nop 1
	v_sub_f32_e32 v162, v0, v70
	v_sub_f32_e32 v163, v1, v71
	v_add_u32_e32 v0, v204, v209
	ds_read_b128 v[100:103], v0 offset:9216
	ds_read_b128 v[104:107], v0 offset:9280
	ds_read_b128 v[92:95], v0 offset:11520
	ds_read_b128 v[96:99], v0 offset:11584
	ds_read_b128 v[84:87], v0 offset:13824
	ds_read_b128 v[88:91], v0 offset:13888
	ds_read_b128 v[76:79], v0 offset:16128
	ds_read_b128 v[80:83], v0 offset:16192
	ds_read_b128 v[222:225], v210 offset:64
	ds_read_b128 v[226:229], v210
	s_waitcnt lgkmcnt(0)
	v_mfma_f32_16x16x32_bf16 v[226:229], v[100:103], v[226:229], 0
	v_sub_f32_e32 v0, v166, v56
	v_mul_f32_e32 v0, 0x3fb8aa3b, v0
	v_exp_f32_e32 v0, v0
	v_mfma_f32_16x16x32_bf16 v[222:225], v[104:107], v[222:225], v[226:229]
	v_sub_f32_e32 v1, v166, v59
	v_mul_f32_e32 v1, 0x3fb8aa3b, v1
	v_exp_f32_e32 v1, v1
	v_sub_f32_e32 v164, v72, v68
	v_sub_f32_e32 v165, v73, v69
	v_cvt_pk_bf16_f32 v72, v158, v159
	s_nop 2
	v_mul_f32_e32 v0, v0, v222
	v_cndmask_b32_e64 v3, v0, 0, s[40:41]
	v_sub_f32_e32 v0, v166, v57
	v_mul_f32_e32 v0, 0x3fb8aa3b, v0
	v_exp_f32_e32 v0, v0
	v_cvt_pk_bf16_f32 v73, v156, v157
	v_cvt_pk_bf16_f32 v75, v150, v151
	v_cvt_pk_bf16_f32 v68, v152, v153
	v_mul_f32_e32 v0, v0, v223
	v_cndmask_b32_e64 v190, 0, v0, s[42:43]
	v_sub_f32_e32 v0, v166, v58
	v_mul_f32_e32 v0, 0x3fb8aa3b, v0
	v_exp_f32_e32 v0, v0
	v_add_u32_e32 v166, v210, v211
	ds_read2_b64 v[230:233], v166 offset0:8 offset1:12
	v_cvt_pk_bf16_f32 v69, v148, v149
	v_mul_f32_e32 v188, v0, v224
	v_mul_f32_e32 v189, v1, v225
	ds_read2_b64 v[222:225], v166 offset1:4
	v_cvt_pk_bf16_f32 v1, v188, v189
	v_cvt_pk_bf16_f32 v0, v3, v190
	v_cndmask_b32_e64 v3, v1, 0, s[46:47]
	v_lshrrev_b32_e32 v1, 16, v1
	v_cndmask_b32_e64 v1, v1, 0, s[44:45]
	v_perm_b32 v1, v1, v3, s0
	v_mov_b32_e32 v3, v2
	s_waitcnt lgkmcnt(0)
	v_mfma_f32_16x16x32_bf16 v[222:225], v[222:225], v[64:67], 0
	v_cvt_pk_bf16_f32 v70, v164, v165
	v_cvt_pk_bf16_f32 v71, v162, v163
	v_sub_f32_e32 v166, v167, v53
	v_mfma_f32_16x16x32_bf16 v[226:229], v[0:3], v[72:75], 0
	v_mul_f32_e32 v0, 0x3fb8aa3b, v56
	v_exp_f32_e32 v0, v0
	v_mul_f32_e32 v166, 0x3fb8aa3b, v166
	v_mfma_f32_16x16x32_bf16 v[222:225], v[230:233], v[60:63], v[222:225]
	v_exp_f32_e32 v166, v166
	v_sub_f32_e32 v3, v167, v58
	v_mul_f32_e32 v3, 0x3fb8aa3b, v3
	v_mfma_f32_16x16x32_bf16 v[226:229], v[108:111], v[68:71], v[226:229]
	v_exp_f32_e32 v188, v3
	v_sub_f32_e32 v3, v167, v59
	v_mul_f32_e32 v3, 0x3fb8aa3b, v3
	v_sub_f32_e32 v1, v167, v57
	v_exp_f32_e32 v189, v3
	s_nop 2
	v_fma_f32 v0, v0, v222, v226
	v_cvt_pk_bf16_f32 v0, v0, s0
	ds_write_b16 v212, v0 offset:35840
	v_mul_f32_e32 v0, 0x3fb8aa3b, v57
	v_exp_f32_e32 v0, v0
	v_sub_f32_e32 v3, v167, v52
	v_mul_f32_e32 v1, 0x3fb8aa3b, v1
	v_mul_f32_e32 v3, 0x3fb8aa3b, v3
	v_fma_f32 v0, v0, v223, v227
	v_cvt_pk_bf16_f32 v0, v0, s0
	ds_write_b16 v212, v0 offset:35984
	v_mul_f32_e32 v0, 0x3fb8aa3b, v58
	v_exp_f32_e32 v0, v0
	v_exp_f32_e32 v1, v1
	v_exp_f32_e32 v3, v3
	v_fma_f32 v0, v0, v224, v228
	v_cvt_pk_bf16_f32 v0, v0, s0
	ds_write_b16 v212, v0 offset:36128
	v_mul_f32_e32 v0, 0x3fb8aa3b, v59
	v_exp_f32_e32 v0, v0
	s_nop 0
	v_fmac_f32_e32 v229, v0, v225
	v_cvt_pk_bf16_f32 v0, v229, s0
	ds_write_b16 v212, v0 offset:36272
	ds_read_b128 v[222:225], v213
	ds_read_b128 v[226:229], v213 offset:64
	s_waitcnt lgkmcnt(1)
	v_mfma_f32_16x16x32_bf16 v[230:233], v[100:103], v[222:225], 0
	v_sub_f32_e32 v0, v167, v56
	v_mul_f32_e32 v0, 0x3fb8aa3b, v0
	v_exp_f32_e32 v0, v0
	v_mfma_f32_16x16x32_bf16 v[222:225], v[92:95], v[222:225], 0
	s_waitcnt lgkmcnt(0)
	v_mfma_f32_16x16x32_bf16 v[222:225], v[96:99], v[226:229], v[222:225]
	v_mfma_f32_16x16x32_bf16 v[230:233], v[104:107], v[226:229], v[230:233]
	s_nop 6
	v_mul_f32_e32 v166, v166, v223
	v_cndmask_b32_e64 v190, v166, 0, s[48:49]
	v_sub_f32_e32 v166, v167, v54
	v_sub_f32_e32 v167, v167, v55
	v_mul_f32_e32 v166, 0x3fb8aa3b, v166
	v_mul_f32_e32 v167, 0x3fb8aa3b, v167
	v_exp_f32_e32 v166, v166
	v_exp_f32_e32 v167, v167
	v_mul_f32_e32 v0, v0, v230
	v_mul_f32_e32 v1, v1, v231
	v_mul_f32_e32 v3, v3, v222
	v_cvt_pk_bf16_f32 v226, v0, v1
	v_mul_f32_e32 v166, v166, v224
	v_mul_f32_e32 v167, v167, v225
	ds_read2_b64 v[222:225], v191 offset1:4
	v_cvt_pk_bf16_f32 v0, v166, v167
	v_cndmask_b32_e64 v1, v0, 0, s[52:53]
	v_lshrrev_b32_e32 v0, 16, v0
	v_mul_f32_e32 v188, v188, v232
	v_mul_f32_e32 v189, v189, v233
	v_cndmask_b32_e64 v3, v3, 0, s[40:41]
	v_cndmask_b32_e64 v0, v0, 0, s[50:51]
	v_cvt_pk_bf16_f32 v227, v188, v189
	v_cvt_pk_bf16_f32 v228, v3, v190
	v_perm_b32 v229, v0, v1, s0
	ds_read2_b64 v[230:233], v191 offset0:8 offset1:12
	s_waitcnt lgkmcnt(1)
	v_mfma_f32_16x16x32_bf16 v[222:225], v[222:225], v[64:67], 0
	v_mul_f32_e32 v0, 0x3fb8aa3b, v52
	v_exp_f32_e32 v0, v0
	v_sub_f32_e32 v3, v160, v58
	v_mfma_f32_16x16x32_bf16 v[226:229], v[226:229], v[72:75], 0
	v_mul_f32_e32 v3, 0x3fb8aa3b, v3
	v_exp_f32_e32 v166, v3
	v_sub_f32_e32 v3, v160, v59
	s_waitcnt lgkmcnt(0)
	v_mfma_f32_16x16x32_bf16 v[222:225], v[230:233], v[60:63], v[222:225]
	v_mul_f32_e32 v3, 0x3fb8aa3b, v3
	v_sub_f32_e32 v1, v160, v57
	v_exp_f32_e32 v167, v3
	v_mfma_f32_16x16x32_bf16 v[108:111], v[108:111], v[68:71], v[226:229]
	v_sub_f32_e32 v3, v160, v52
	v_mul_f32_e32 v1, 0x3fb8aa3b, v1
	v_mul_f32_e32 v3, 0x3fb8aa3b, v3
	v_exp_f32_e32 v1, v1
	v_exp_f32_e32 v188, v3
	s_nop 2
	v_fma_f32 v0, v0, v222, v108
	v_cvt_pk_bf16_f32 v0, v0, s0
	ds_write_b16 v212, v0 offset:38144
	v_mul_f32_e32 v0, 0x3fb8aa3b, v53
	v_exp_f32_e32 v0, v0
	v_sub_f32_e32 v3, v160, v53
	v_mul_f32_e32 v3, 0x3fb8aa3b, v3
	v_exp_f32_e32 v189, v3
	v_fma_f32 v0, v0, v223, v109
	v_cvt_pk_bf16_f32 v0, v0, s0
	ds_write_b16 v212, v0 offset:38288
	v_mul_f32_e32 v0, 0x3fb8aa3b, v54
	v_exp_f32_e32 v0, v0
	v_sub_f32_e32 v3, v160, v54
	v_mul_f32_e32 v3, 0x3fb8aa3b, v3
	v_exp_f32_e32 v190, v3
	v_fma_f32 v0, v0, v224, v110
	v_cvt_pk_bf16_f32 v0, v0, s0
	ds_write_b16 v212, v0 offset:38432
	v_mul_f32_e32 v0, 0x3fb8aa3b, v55
	v_exp_f32_e32 v0, v0
	v_sub_f32_e32 v3, v160, v55
	v_mul_f32_e32 v3, 0x3fb8aa3b, v3
	v_exp_f32_e32 v191, v3
	v_fmac_f32_e32 v111, v0, v225
	v_cvt_pk_bf16_f32 v0, v111, s0
	ds_write_b16 v212, v0 offset:38576
	ds_read_b128 v[108:111], v214
	ds_read_b128 v[222:225], v214 offset:64
	s_waitcnt lgkmcnt(1)
	v_mfma_f32_16x16x32_bf16 v[226:229], v[100:103], v[108:111], 0
	v_sub_f32_e32 v0, v160, v56
	v_mul_f32_e32 v0, 0x3fb8aa3b, v0
	v_exp_f32_e32 v0, v0
	s_waitcnt lgkmcnt(0)
	v_mfma_f32_16x16x32_bf16 v[226:229], v[104:107], v[222:225], v[226:229]
	v_sub_f32_e32 v3, v160, v48
	v_mul_f32_e32 v3, 0x3fb8aa3b, v3
	v_exp_f32_e32 v3, v3
	s_nop 4
	v_mul_f32_e32 v0, v0, v226
	v_mul_f32_e32 v1, v1, v227
	v_mul_f32_e32 v166, v166, v228
	v_mul_f32_e32 v167, v167, v229
	v_mfma_f32_16x16x32_bf16 v[226:229], v[92:95], v[108:111], 0
	v_mfma_f32_16x16x32_bf16 v[108:111], v[84:87], v[108:111], 0
	v_mfma_f32_16x16x32_bf16 v[108:111], v[88:91], v[222:225], v[108:111]
	v_mfma_f32_16x16x32_bf16 v[226:229], v[96:99], v[222:225], v[226:229]
	v_cvt_pk_bf16_f32 v222, v0, v1
	s_nop 5
	v_mul_f32_e32 v3, v3, v108
	v_sub_f32_e32 v108, v160, v49
	v_mul_f32_e32 v108, 0x3fb8aa3b, v108
	v_exp_f32_e32 v108, v108
	v_mul_f32_e32 v188, v188, v226
	v_mul_f32_e32 v189, v189, v227
	v_mul_f32_e32 v190, v190, v228
	v_mul_f32_e32 v191, v191, v229
	v_cvt_pk_bf16_f32 v223, v166, v167
	v_mul_f32_e32 v108, v108, v109
	v_cndmask_b32_e64 v221, v108, 0, s[54:55]
	v_sub_f32_e32 v108, v160, v50
	v_sub_f32_e32 v109, v160, v51
	v_mul_f32_e32 v108, 0x3fb8aa3b, v108
	v_mul_f32_e32 v109, 0x3fb8aa3b, v109
	v_exp_f32_e32 v108, v108
	v_exp_f32_e32 v109, v109
	v_add_u32_e32 v160, v214, v211
	v_cvt_pk_bf16_f32 v224, v188, v189
	v_cvt_pk_bf16_f32 v225, v190, v191
	v_mul_f32_e32 v230, v108, v110
	v_mul_f32_e32 v231, v109, v111
	ds_read2_b64 v[108:111], v160 offset1:4
	v_cndmask_b32_e64 v3, v3, 0, s[40:41]
	ds_read2_b64 v[226:229], v160 offset0:8 offset1:12
	v_cvt_pk_bf16_f32 v1, v230, v231
	v_cvt_pk_bf16_f32 v0, v3, v221
	v_cndmask_b32_e64 v3, v1, 0, s[58:59]
	v_lshrrev_b32_e32 v1, 16, v1
	v_cndmask_b32_e64 v1, v1, 0, s[56:57]
	v_perm_b32 v1, v1, v3, s0
	v_mov_b32_e32 v3, v2
	v_mfma_f32_16x16x32_bf16 v[222:225], v[222:225], v[72:75], 0
	s_waitcnt lgkmcnt(1)
	v_mfma_f32_16x16x32_bf16 v[108:111], v[108:111], v[64:67], 0
	v_mfma_f32_16x16x32_bf16 v[222:225], v[0:3], v[68:71], v[222:225]
	v_mul_f32_e32 v0, 0x3fb8aa3b, v48
	v_exp_f32_e32 v0, v0
	v_sub_f32_e32 v1, v161, v57
	s_waitcnt lgkmcnt(0)
	v_mfma_f32_16x16x32_bf16 v[108:111], v[226:229], v[60:63], v[108:111]
	v_mul_f32_e32 v1, 0x3fb8aa3b, v1
	v_exp_f32_e32 v1, v1
	v_sub_f32_e32 v3, v161, v58
	v_mul_f32_e32 v3, 0x3fb8aa3b, v3
	s_nop 3
	v_fma_f32 v0, v0, v108, v222
	v_cvt_pk_bf16_f32 v0, v0, s0
	ds_write_b16 v212, v0 offset:40448
	v_mul_f32_e32 v0, 0x3fb8aa3b, v49
	v_exp_f32_e32 v0, v0
	s_nop 0
	v_fma_f32 v0, v0, v109, v223
	v_cvt_pk_bf16_f32 v0, v0, s0
	ds_write_b16 v212, v0 offset:40592
	v_mul_f32_e32 v0, 0x3fb8aa3b, v50
	v_exp_f32_e32 v0, v0
	s_nop 0
	v_fma_f32 v0, v0, v110, v224
	v_cvt_pk_bf16_f32 v0, v0, s0
	ds_write_b16 v212, v0 offset:40736
	v_mul_f32_e32 v0, 0x3fb8aa3b, v51
	v_exp_f32_e32 v0, v0
	s_nop 0
	v_fmac_f32_e32 v225, v0, v111
	v_cvt_pk_bf16_f32 v0, v225, s0
	ds_write_b16 v212, v0 offset:40880
	ds_read_b128 v[108:111], v215
	ds_read_b128 v[222:225], v215 offset:64
	s_waitcnt lgkmcnt(1)
	v_mfma_f32_16x16x32_bf16 v[100:103], v[100:103], v[108:111], 0
	v_sub_f32_e32 v0, v161, v56
	v_mul_f32_e32 v0, 0x3fb8aa3b, v0
	v_exp_f32_e32 v0, v0
	s_waitcnt lgkmcnt(0)
	v_mfma_f32_16x16x32_bf16 v[100:103], v[104:107], v[222:225], v[100:103]
	v_mfma_f32_16x16x32_bf16 v[92:95], v[92:95], v[108:111], 0
	v_mfma_f32_16x16x32_bf16 v[92:95], v[96:99], v[222:225], v[92:95]
	s_nop 5
	v_mul_f32_e64 v0, v0, v100
	v_mul_f32_e64 v1, v1, v101
	v_exp_f32_e32 v100, v3
	v_sub_f32_e32 v3, v161, v59
	v_mul_f32_e32 v3, 0x3fb8aa3b, v3
	v_exp_f32_e32 v101, v3
	v_sub_f32_e32 v3, v161, v52
	v_mul_f32_e32 v3, 0x3fb8aa3b, v3
	v_exp_f32_e32 v96, v3
	v_sub_f32_e32 v3, v161, v53
	v_mul_f32_e32 v3, 0x3fb8aa3b, v3
	v_exp_f32_e32 v97, v3
	v_sub_f32_e32 v3, v161, v54
	v_mul_f32_e32 v3, 0x3fb8aa3b, v3
	v_mfma_f32_16x16x32_bf16 v[84:87], v[84:87], v[108:111], 0
	v_mul_f32_e64 v92, v96, v92
	v_mul_f32_e64 v93, v97, v93
	v_exp_f32_e32 v96, v3
	v_sub_f32_e32 v3, v161, v55
	v_mul_f32_e32 v3, 0x3fb8aa3b, v3
	v_exp_f32_e32 v97, v3
	v_sub_f32_e32 v3, v161, v48
	v_mul_f32_e32 v3, 0x3fb8aa3b, v3
	v_mfma_f32_16x16x32_bf16 v[84:87], v[88:91], v[222:225], v[84:87]
	v_exp_f32_e32 v88, v3
	v_sub_f32_e32 v3, v161, v49
	v_mul_f32_e32 v3, 0x3fb8aa3b, v3
	v_exp_f32_e32 v89, v3
	v_sub_f32_e32 v3, v161, v50
	v_mul_f32_e32 v3, 0x3fb8aa3b, v3
	v_mfma_f32_16x16x32_bf16 v[76:79], v[76:79], v[108:111], 0
	s_nop 0
	v_mul_f32_e64 v84, v88, v84
	v_mul_f32_e64 v85, v89, v85
	v_exp_f32_e32 v88, v3
	v_sub_f32_e32 v3, v161, v51
	v_mul_f32_e32 v3, 0x3fb8aa3b, v3
	v_exp_f32_e32 v89, v3
	v_sub_f32_e32 v3, v161, v44
	v_mul_f32_e32 v3, 0x3fb8aa3b, v3
	v_mfma_f32_16x16x32_bf16 v[76:79], v[80:83], v[222:225], v[76:79]
	v_exp_f32_e32 v3, v3
	v_add_u32_e32 v83, v215, v211
	v_mul_f32_e32 v100, v100, v102
	v_mul_f32_e32 v101, v101, v103
	v_mul_f32_e32 v94, v96, v94
	v_mul_f32_e32 v95, v97, v95
	v_mul_f32_e32 v86, v88, v86
	v_mul_f32_e32 v87, v89, v87
	s_nop 2
	v_mul_f32_e32 v3, v3, v76
	v_sub_f32_e32 v76, v161, v45
	v_mul_f32_e32 v76, 0x3fb8aa3b, v76
	v_exp_f32_e32 v76, v76
	v_cndmask_b32_e64 v3, v3, 0, s[40:41]
	v_mul_f32_e32 v76, v76, v77
	v_cndmask_b32_e64 v82, v76, 0, s[60:61]
	v_sub_f32_e32 v76, v161, v46
	v_sub_f32_e32 v77, v161, v47
	v_mul_f32_e32 v76, 0x3fb8aa3b, v76
	v_mul_f32_e32 v77, 0x3fb8aa3b, v77
	v_exp_f32_e32 v76, v76
	v_exp_f32_e32 v77, v77
	s_nop 0
	v_mul_f32_e32 v80, v76, v78
	v_mul_f32_e32 v81, v77, v79
	ds_read2_b64 v[76:79], v83 offset1:4
	s_waitcnt lgkmcnt(0)
	v_mfma_f32_16x16x32_bf16 v[64:67], v[76:79], v[64:67], 0
	v_cvt_pk_bf16_f32 v76, v0, v1
	v_cvt_pk_bf16_f32 v77, v100, v101
	v_cvt_pk_bf16_f32 v78, v92, v93
	v_cvt_pk_bf16_f32 v79, v94, v95
	v_cvt_pk_bf16_f32 v0, v80, v81
	v_cndmask_b32_e64 v1, v0, 0, s[64:65]
	v_mfma_f32_16x16x32_bf16 v[72:75], v[76:79], v[72:75], 0
	ds_read2_b64 v[76:79], v83 offset0:8 offset1:12
	v_lshrrev_b32_e32 v0, 16, v0
	v_cndmask_b32_e64 v0, v0, 0, s[62:63]
	s_waitcnt lgkmcnt(0)
	v_mfma_f32_16x16x32_bf16 v[60:63], v[76:79], v[60:63], v[64:67]
	s_nop 2
	v_cvt_pk_bf16_f32 v64, v84, v85
	v_cvt_pk_bf16_f32 v65, v86, v87
	v_cvt_pk_bf16_f32 v66, v3, v82
	v_perm_b32 v67, v0, v1, s0
	v_mul_f32_e32 v0, 0x3fb8aa3b, v44
	v_exp_f32_e32 v0, v0
	v_mfma_f32_16x16x32_bf16 v[64:67], v[64:67], v[68:71], v[72:75]
	v_sub_f32_e32 v3, v220, v58
	v_mul_f32_e32 v3, 0x3fb8aa3b, v3
	v_sub_f32_e32 v1, v220, v57
	s_nop 4
	v_fma_f32 v0, v0, v60, v64
	v_cvt_pk_bf16_f32 v0, v0, s0
	ds_write_b16 v212, v0 offset:42752
	v_mul_f32_e32 v0, 0x3fb8aa3b, v45
	v_exp_f32_e32 v0, v0
	v_mul_f32_e32 v1, 0x3fb8aa3b, v1
	v_exp_f32_e32 v1, v1
	s_waitcnt vmcnt(1)
	v_mov_b64_e32 v[68:69], v[144:145]
	v_fma_f32 v0, v0, v61, v65
	v_cvt_pk_bf16_f32 v0, v0, s0
	ds_write_b16 v216, v0 offset:35840
	v_mul_f32_e32 v0, 0x3fb8aa3b, v46
	v_exp_f32_e32 v0, v0
	v_mov_b64_e32 v[70:71], v[142:143]
	v_mov_b64_e32 v[72:73], v[140:141]
	v_fma_f32 v0, v0, v62, v66
	v_cvt_pk_bf16_f32 v0, v0, s0
	ds_write_b16 v217, v0 offset:35840
	v_mul_f32_e32 v0, 0x3fb8aa3b, v47
	v_exp_f32_e32 v0, v0
	s_nop 0
	v_fmac_f32_e32 v67, v0, v63
	v_cvt_pk_bf16_f32 v0, v67, s0
	ds_write_b16 v218, v0 offset:35840
	v_sub_f32_e32 v0, v220, v56
	v_exp_f32_e32 v56, v3
	v_sub_f32_e32 v3, v220, v59
	v_mul_f32_e32 v3, 0x3fb8aa3b, v3
	v_exp_f32_e32 v57, v3
	v_sub_f32_e32 v3, v220, v52
	v_mul_f32_e32 v3, 0x3fb8aa3b, v3
	v_exp_f32_e32 v52, v3
	v_sub_f32_e32 v3, v220, v53
	v_mul_f32_e32 v3, 0x3fb8aa3b, v3
	v_exp_f32_e32 v53, v3
	v_sub_f32_e32 v3, v220, v54
	v_mul_f32_e32 v3, 0x3fb8aa3b, v3
	v_exp_f32_e32 v54, v3
	v_sub_f32_e32 v3, v220, v55
	v_mul_f32_e32 v3, 0x3fb8aa3b, v3
	v_exp_f32_e32 v55, v3
	v_sub_f32_e32 v3, v220, v48
	v_mul_f32_e32 v3, 0x3fb8aa3b, v3
	v_exp_f32_e32 v48, v3
	v_sub_f32_e32 v3, v220, v49
	v_mul_f32_e32 v3, 0x3fb8aa3b, v3
	v_exp_f32_e32 v49, v3
	v_sub_f32_e32 v3, v220, v50
	v_mul_f32_e32 v3, 0x3fb8aa3b, v3
	v_exp_f32_e32 v50, v3
	v_sub_f32_e32 v3, v220, v51
	v_mul_f32_e32 v3, 0x3fb8aa3b, v3
	v_exp_f32_e32 v51, v3
	v_sub_f32_e32 v3, v220, v44
	v_mul_f32_e32 v3, 0x3fb8aa3b, v3
	v_exp_f32_e32 v44, v3
	v_sub_f32_e32 v3, v220, v45
	v_mul_f32_e32 v3, 0x3fb8aa3b, v3
	v_exp_f32_e32 v45, v3
	v_sub_f32_e32 v3, v220, v46
	v_mul_f32_e32 v3, 0x3fb8aa3b, v3
	v_mul_f32_e32 v0, 0x3fb8aa3b, v0
	v_mul_f32_e32 v58, v44, v164
	v_mul_f32_e32 v59, v45, v165
	v_exp_f32_e32 v44, v3
	v_sub_f32_e32 v3, v220, v47
	v_exp_f32_e32 v0, v0
	v_mul_f32_e32 v3, 0x3fb8aa3b, v3
	v_exp_f32_e32 v45, v3
	v_mul_f32_e32 v52, v52, v154
	v_mul_f32_e32 v53, v53, v155
	v_mul_f32_e32 v0, v0, v158
	v_mul_f32_e32 v1, v1, v159
	v_mul_f32_e32 v54, v54, v150
	v_mul_f32_e32 v55, v55, v151
	v_mul_f32_e32 v60, v44, v162
	v_mul_f32_e32 v61, v45, v163
	v_cvt_pk_bf16_f32 v44, v0, v1
	v_mul_f32_e32 v0, 0x3fb8aa3b, v220
	v_exp_f32_e32 v0, v0
	v_cvt_pk_bf16_f32 v46, v52, v53
	v_cvt_pk_bf16_f32 v47, v54, v55
	v_mul_f32_e32 v56, v56, v156
	v_mul_f32_e32 v57, v57, v157
	v_mul_f32_e32 v26, v26, v0
	v_mul_f32_e32 v27, v27, v0
	v_mul_f32_e32 v24, v24, v0
	v_mul_f32_e32 v25, v25, v0
	v_add_u32_e32 v1, v206, v209
	v_add_u32_e32 v3, 0x5800, v1
	v_cvt_pk_bf16_f32 v45, v56, v57
	v_mul_f32_e32 v48, v48, v152
	v_mul_f32_e32 v49, v49, v153
	v_mul_f32_e32 v50, v50, v148
	v_mul_f32_e32 v51, v51, v149
	s_waitcnt lgkmcnt(0)
	v_mfma_f32_16x16x32_bf16 v[24:27], v[234:237], v[44:47], v[24:27]
	ds_read2_b64 v[234:237], v3 offset0:64 offset1:68
	v_cvt_pk_bf16_f32 v48, v48, v49
	v_cvt_pk_bf16_f32 v49, v50, v51
	v_cvt_pk_bf16_f32 v50, v58, v59
	v_cvt_pk_bf16_f32 v51, v60, v61
	v_mul_f32_e32 v6, v6, v0
	v_mul_f32_e32 v7, v7, v0
	v_mul_f32_e32 v4, v4, v0
	v_mul_f32_e32 v5, v5, v0
	v_mfma_f32_16x16x32_bf16 v[24:27], v[238:241], v[48:51], v[24:27]
	ds_read2_b64 v[238:241], v3 offset0:72 offset1:76
	v_mul_f32_e32 v10, v10, v0
	v_mul_f32_e32 v11, v11, v0
	v_mul_f32_e32 v8, v8, v0
	v_mul_f32_e32 v9, v9, v0
	v_mfma_f32_16x16x32_bf16 v[4:7], v[242:245], v[44:47], v[4:7]
	v_mul_f32_e32 v14, v14, v0
	v_mul_f32_e32 v15, v15, v0
	v_mul_f32_e32 v12, v12, v0
	v_mul_f32_e32 v13, v13, v0
	v_add_u32_e32 v0, 0x6000, v1
	ds_read2_b64 v[242:245], v0 offset0:96 offset1:100
	v_mfma_f32_16x16x32_bf16 v[4:7], v[246:249], v[48:51], v[4:7]
	ds_read2_b64 v[246:249], v0 offset0:104 offset1:108
	s_waitcnt lgkmcnt(3)
	v_mfma_f32_16x16x32_bf16 v[8:11], v[234:237], v[44:47], v[8:11]
	s_waitcnt lgkmcnt(2)
	v_mfma_f32_16x16x32_bf16 v[8:11], v[238:241], v[48:51], v[8:11]
	s_waitcnt lgkmcnt(1)
	v_mfma_f32_16x16x32_bf16 v[12:15], v[242:245], v[44:47], v[12:15]
	s_waitcnt vmcnt(0)
	v_mov_b64_e32 v[0:1], v[146:147]
	s_waitcnt lgkmcnt(0)
	v_mfma_f32_16x16x32_bf16 v[12:15], v[246:249], v[48:51], v[12:15]
